# P0 W_in transpose uses the LDS-free dwordx4 item code (one latency per item instead of five)
# speedup vs baseline: 1.0209x; 1.0007x over previous
; #define GAS __attribute__((address_space(1)))
; #define LAS __attribute__((address_space(3)))
; #define LDS_WAIT() asm volatile("s_waitcnt lgkmcnt(0)" ::: "memory")
; __device__ __forceinline__ unsigned pk2(float lo, float hi) { return f2bf(lo) | (f2bf(hi) << 16); }
; __device__ __forceinline__ void p0_transpose_item(const float* W, int K, int N, bf16* WT, const float* gain, int mode, LAS float* scr, int item, int lane) {
;     const int nblk = N / 32, kb = item / nblk, nb = item % nblk, k0 = 64 * kb, n0 = 32 * nb;
; #pragma unroll 8
;     for (int i = 0; i < 32; ++i) { const int kk = 2 * i + (lane >> 5); scr[kk * 33 + (lane & 31)] = __builtin_nontemporal_load(W + (size_t)(k0 + kk) * N + n0 + (lane & 31)); }
;     LDS_WAIT(); asm volatile("" ::: "memory");
;     const int c = lane & 7;
;     float g[8];
; #pragma unroll
;     for (int i = 0; i < 8; ++i) g[i] = gain ? gain[k0 + 8 * c + i] : 1.0f;
;     const int rbase = (mode == 0) ? n0 : (256 * (n0 >> 7) + (n0 & 127) + (mode == 2 ? 128 : 0));
; #pragma unroll
;     for (int j = 0; j < 4; ++j) { const int n = (lane >> 3) + 8 * j; const LAS float* s = scr + (8 * c) * 33 + n;
;         v4u o; o.x = pk2(s[0 * 33] * g[0], s[1 * 33] * g[1]); o.y = pk2(s[2 * 33] * g[2], s[3 * 33] * g[3]); o.z = pk2(s[4 * 33] * g[4], s[5 * 33] * g[5]); o.w = pk2(s[6 * 33] * g[6], s[7 * 33] * g[7]);
;         *(GAS v4u*)(WT + (size_t)(rbase + n) * K + k0 + 8 * c) = o; }
; __device__ __forceinline__ void p0_prologue(Frame& F) {
;     ...
;     constexpr int I_IN = (D / 64) * (PW / 32);
;     for (int it = gw; it < I_IN; it += NGW) p0_transpose_item(F.w_in, D, PW, F.WIN, F.g1, 0, scr, it, F.lane);
.LBB0_11:
	s_or_b64 exec, exec, s[4:5]
	s_lshr_b32 s94, s62, 6
	s_add_u32 s20, s58, 0x200000
	s_addc_u32 s21, s59, 0
	s_load_dwordx16 s[36:51], s[0:1], 0x0
	s_cmp_lt_i32 s56, 1
	s_cselect_b64 s[0:1], -1, 0
	s_cmp_gt_i32 s57, 0
	s_cselect_b64 s[4:5], -1, 0
	s_and_b64 s[0:1], s[0:1], s[4:5]
	s_andn2_b64 vcc, exec, s[0:1]
	v_and_b32_e32 v206, 63, v0
	s_cbranch_vccnz .LBB0_92
	s_lshl_b32 s0, s2, 3
	s_add_i32 s6, s94, s0
	s_lshl_b32 s8, s3, 3
	s_cmpk_gt_i32 s6, 0x57f
	s_cbranch_scc1 .LBB0_33
	s_waitcnt lgkmcnt(0)
	v_lshrrev_b32_e32 v94, 3, v206
	v_and_b32_e32 v95, 7, v206
	v_lshlrev_b32_e32 v108, 5, v94
	v_mul_u32_u24_e32 v96, 0x16000, v94
	v_lshl_add_u32 v96, v95, 4, v96
	v_add_u32_e32 v97, 0x2c00, v96
	v_add_u32_e32 v98, 0x5800, v96
	v_add_u32_e32 v99, 0x8400, v96
	v_add_u32_e32 v100, 0xb000, v96
	v_add_u32_e32 v101, 0xdc00, v96
	v_add_u32_e32 v102, 0x10800, v96
	v_add_u32_e32 v103, 0x13400, v96
	v_mul_u32_u24_e32 v104, 0x2000, v95
	v_lshl_add_u32 v104, v94, 4, v104
	v_add_u32_e32 v105, 0x800, v104
	v_add_u32_e32 v106, 0x1000, v104
	v_add_u32_e32 v107, 0x1800, v104
	s_add_u32 s84, s58, 0x200000
	s_addc_u32 s85, s59, 0
	s_mov_b32 s64, s6
	s_cmp_lt_i32 s64, 1408
	s_cbranch_scc0 .Lht_p0_0_done
.Lht_p0_0_loop:
	s_mov_b32 s65, s64
	s_mov_b32 s76, s40
	s_mov_b32 s77, s41
	s_mul_hi_u32 s66, s65, 0x2e8ba2f
	s_mul_i32 s68, s66, 88
	s_sub_i32 s67, s65, s68
	s_mul_i32 s68, s66, 0xb0000
	s_lshl_b32 s69, s67, 7
	s_add_i32 s68, s68, s69
	s_add_u32 s76, s76, s68
	s_addc_u32 s77, s77, 0
	s_lshl_b32 s68, s67, 5
	s_mul_i32 s68, s68, 0x800
	s_lshl_b32 s69, s66, 7
	s_add_i32 s68, s68, s69
	s_add_u32 s78, s84, s68
	s_addc_u32 s79, s85, 0
	s_lshl_b32 s68, s66, 8
	s_add_u32 s82, s38, s68
	s_addc_u32 s83, s39, 0
	global_load_dwordx4 v[110:113], v96, s[76:77] nt
	global_load_dwordx4 v[114:117], v97, s[76:77] nt
	global_load_dwordx4 v[118:121], v98, s[76:77] nt
	global_load_dwordx4 v[122:125], v99, s[76:77] nt
	global_load_dwordx4 v[126:129], v100, s[76:77] nt
	global_load_dwordx4 v[130:133], v101, s[76:77] nt
	global_load_dwordx4 v[134:137], v102, s[76:77] nt
	global_load_dwordx4 v[138:141], v103, s[76:77] nt
	global_load_dwordx4 v[142:145], v108, s[82:83]
	global_load_dwordx4 v[146:149], v108, s[82:83] offset:16
	s_waitcnt vmcnt(0)
	v_mul_f32_e32 v110, v110, v142
	v_mul_f32_e32 v111, v111, v142
	v_mul_f32_e32 v112, v112, v142
	v_mul_f32_e32 v113, v113, v142
	v_mul_f32_e32 v114, v114, v143
	v_mul_f32_e32 v115, v115, v143
	v_mul_f32_e32 v116, v116, v143
	v_mul_f32_e32 v117, v117, v143
	v_mul_f32_e32 v118, v118, v144
	v_mul_f32_e32 v119, v119, v144
	v_mul_f32_e32 v120, v120, v144
	v_mul_f32_e32 v121, v121, v144
	v_mul_f32_e32 v122, v122, v145
	v_mul_f32_e32 v123, v123, v145
	v_mul_f32_e32 v124, v124, v145
	v_mul_f32_e32 v125, v125, v145
	v_mul_f32_e32 v126, v126, v146
	v_mul_f32_e32 v127, v127, v146
	v_mul_f32_e32 v128, v128, v146
	v_mul_f32_e32 v129, v129, v146
	v_mul_f32_e32 v130, v130, v147
	v_mul_f32_e32 v131, v131, v147
	v_mul_f32_e32 v132, v132, v147
	v_mul_f32_e32 v133, v133, v147
	v_mul_f32_e32 v134, v134, v148
	v_mul_f32_e32 v135, v135, v148
	v_mul_f32_e32 v136, v136, v148
	v_mul_f32_e32 v137, v137, v148
	v_mul_f32_e32 v138, v138, v149
	v_mul_f32_e32 v139, v139, v149
	v_mul_f32_e32 v140, v140, v149
	v_mul_f32_e32 v141, v141, v149
	v_cvt_pk_bf16_f32 v150, v110, v114
	v_cvt_pk_bf16_f32 v151, v118, v122
	v_cvt_pk_bf16_f32 v152, v126, v130
	v_cvt_pk_bf16_f32 v153, v134, v138
	v_cvt_pk_bf16_f32 v154, v111, v115
	v_cvt_pk_bf16_f32 v155, v119, v123
	v_cvt_pk_bf16_f32 v156, v127, v131
	v_cvt_pk_bf16_f32 v157, v135, v139
	v_cvt_pk_bf16_f32 v158, v112, v116
	v_cvt_pk_bf16_f32 v159, v120, v124
	v_cvt_pk_bf16_f32 v160, v128, v132
	v_cvt_pk_bf16_f32 v161, v136, v140
	v_cvt_pk_bf16_f32 v162, v113, v117
	v_cvt_pk_bf16_f32 v163, v121, v125
	v_cvt_pk_bf16_f32 v164, v129, v133
	v_cvt_pk_bf16_f32 v165, v137, v141
	global_store_dwordx4 v104, v[150:153], s[78:79]
	global_store_dwordx4 v105, v[154:157], s[78:79]
	global_store_dwordx4 v106, v[158:161], s[78:79]
	global_store_dwordx4 v107, v[162:165], s[78:79]
	s_mul_i32 s65, s8, 1
	s_add_i32 s64, s64, s65
	s_cmp_lt_i32 s64, 1408
	s_cbranch_scc1 .Lht_p0_0_loop
.Lht_p0_0_done:
.LBB0_33:
	s_cmpk_gt_i32 s6, 0x3fff
	s_cbranch_scc1 .LBB0_38
	v_mbcnt_lo_u32_b32 v1, -1, 0
	v_mbcnt_hi_u32_b32 v2, -1, v1
	v_and_b32_e32 v1, 64, v2
	v_add_u32_e32 v3, 64, v1
	v_xor_b32_e32 v1, 1, v2
	v_cmp_lt_i32_e32 vcc, v1, v3
	v_xor_b32_e32 v4, 2, v2
	s_ashr_i32 s7, s6, 31
	v_cndmask_b32_e32 v1, v2, v1, vcc
	v_cmp_lt_i32_e32 vcc, v4, v3
	s_lshl_b64 s[4:5], s[6:7], 2
	s_add_u32 s30, s4, 0x1b00000
	v_cndmask_b32_e32 v4, v2, v4, vcc
	v_lshlrev_b32_e32 v24, 2, v4
	v_xor_b32_e32 v4, 4, v2
	v_cmp_lt_i32_e32 vcc, v4, v3
	s_addc_u32 s31, s5, 0
	s_ashr_i32 s9, s8, 31
	v_cndmask_b32_e32 v4, v2, v4, vcc
	v_lshlrev_b32_e32 v25, 2, v4
	v_xor_b32_e32 v4, 8, v2
	v_cmp_lt_i32_e32 vcc, v4, v3
	s_lshl_b64 s[4:5], s[6:7], 11
	s_lshl_b64 s[10:11], s[8:9], 2
	v_cndmask_b32_e32 v4, v2, v4, vcc
	v_lshlrev_b32_e32 v26, 2, v4
	v_xor_b32_e32 v4, 16, v2
	v_cmp_lt_i32_e32 vcc, v4, v3
	v_lshl_or_b32 v18, v206, 3, s4
	v_mov_b32_e32 v19, s5
	v_cndmask_b32_e32 v4, v2, v4, vcc
	v_lshlrev_b32_e32 v27, 2, v4
	v_xor_b32_e32 v4, 32, v2
	s_lshl_b64 s[22:23], s[8:9], 11
	s_lshl_b64 s[4:5], s[6:7], 12
	v_cmp_lt_i32_e32 vcc, v4, v3
	s_waitcnt lgkmcnt(0)
	s_add_u32 s4, s36, s4
	v_lshlrev_b32_e32 v20, 4, v206
	v_cndmask_b32_e32 v2, v2, v4, vcc
	v_mov_b32_e32 v21, 0
	s_addc_u32 s5, s37, s5
	v_lshlrev_b32_e32 v28, 2, v2
	v_lshl_add_u64 v[2:3], s[4:5], 0, v[20:21]
	s_mov_b64 s[4:5], 0xc00
	v_lshlrev_b32_e32 v1, 2, v1
	v_cmp_eq_u32_e64 s[0:1], 0, v206
	v_lshl_add_u64 v[22:23], v[2:3], 0, s[4:5]
	s_lshl_b64 s[24:25], s[8:9], 12
	v_mov_b32_e32 v20, 0x358637bd
	s_mov_b32 s7, 0xf800000
	v_mov_b32_e32 v29, 0x260
	s_movk_i32 s9, 0x7fff
	s_mov_b32 s33, 0xffff0000
	s_brev_b32 s34, 64
	s_branch .LBB0_36
